# v21 + attn_combine: contiguous per-WG ranges sized by the WG's boundary-scan load in the same phase
# speedup vs baseline: 1.0044x; 1.0001x over previous
; __device__ __forceinline__ int ltid(int wave) { int t = (wave << 6) | (int)__builtin_amdgcn_mbcnt_hi(~0u, __builtin_amdgcn_mbcnt_lo(~0u, 0u)); asm volatile("" : "+v"(t)); return t; }
; __device__ __forceinline__ int lbid() { int b = blockIdx.x; asm volatile("" : "+s"(b)); return b; }
; __device__ __forceinline__ u32x4 pack8(f32x4 v0, f32x4 v1) { u32x4 w; w.x = cvt_pk_bf16(v0[0], v0[1]); w.y = cvt_pk_bf16(v0[2], v0[3]); w.z = cvt_pk_bf16(v1[0], v1[1]); w.w = cvt_pk_bf16(v1[2], v1[3]); return w; }
; __device__ __forceinline__ void unpack8(u32x4 w, f32x4& v0, f32x4& v1) { v0 = (f32x4){bflo(w.x), bfhi(w.x), bflo(w.y), bfhi(w.y)}; v1 = (f32x4){bflo(w.z), bfhi(w.z), bflo(w.w), bfhi(w.w)}; }
; __device__ void attn_combine(const Params& p) {
;     ...
;     for (int e = lbid() * 512 + ltid(p.wave); e < MT * 64; e += gridDim.x * 512) {
;         const int tok = e >> 6, h = (e >> 3) & 7, c8 = e & 7;
;         const float l0 = LSE[(size_t)tok * 24 + h], l1 = LSE[(size_t)tok * 24 + 8 + h], l2 = LSE[(size_t)tok * 24 + 16 + h];
;         const float m = fmaxf(l0, fmaxf(l1, l2)); float w0 = __expf(l0 - m), w1 = __expf(l1 - m), w2 = __expf(l2 - m); const float inv = 1.0f / (w0 + w1 + w2); w0 *= inv; w1 *= inv; w2 *= inv;
;         f32x4 a0, a1, b0, b1, c0, c1;
;         const u32x4 ua = *(const u32x4*)(Ab + (size_t)tok * 1536 + h * 64 + c8 * 8), ub = *(const u32x4*)(Ab + (size_t)tok * 1536 + (8 + h) * 64 + c8 * 8), uc = *(const u32x4*)(Ab + (size_t)tok * 1536 + (16 + h) * 64 + c8 * 8);
;         asm volatile("" ::: "memory");
;         unpack8(ua, a0, a1); unpack8(ub, b0, b1); unpack8(uc, c0, c1);
;         *(u32x4*)(YA + (size_t)tok * 512 + h * 64 + c8 * 8) = pack8(a0 * w0 + b0 * w1 + c0 * w2, a1 * w0 + b1 * w1 + c1 * w2);
;     }
.LBB0_256:
	s_mov_b32 s0, s80
	v_mov_b32_e32 v0, v60
	s_mov_b32 s1, 0x180000
	s_waitcnt lgkmcnt(0)
	s_lshl_b32 s2, s0, 2
	s_movk_i32 s3, 4
	s_cmpk_lt_i32 s0, 0x80
	s_cbranch_scc1 .Lcmb_set
	s_sub_i32 s2, s0, 0x80
	s_mul_i32 s2, s2, 18
	s_addk_i32 s2, 0x200
	s_movk_i32 s3, 18
	s_cmpk_lt_i32 s0, 0xc0
	s_cbranch_scc1 .Lcmb_set
	s_sub_i32 s2, s0, 0xc0
	s_mul_i32 s2, s2, 24
	s_addk_i32 s2, 0x680
	s_movk_i32 s3, 24
	s_cmpk_lt_i32 s0, 0xd0
	s_cbranch_scc1 .Lcmb_set
	s_sub_i32 s2, s0, 0xd0
	s_lshl_b32 s2, s2, 2
	s_addk_i32 s2, 0x800
	s_movk_i32 s3, 4
	s_cmpk_lt_i32 s0, 0xd4
	s_cbranch_scc1 .Lcmb_set
	s_sub_i32 s2, s0, 0xd4
	s_mul_i32 s2, s2, 23
	s_addk_i32 s2, 0x810
	s_movk_i32 s3, 23
.Lcmb_set:
	s_add_i32 s3, s2, s3
	s_min_i32 s3, s3, 0xc00
	s_lshl_b32 s3, s3, 9
	v_lshl_add_u32 v2, s2, 9, v0
	v_cmp_gt_i32_e32 vcc, s3, v2
	s_and_saveexec_b64 s[36:37], vcc
	v_readlane_b32 s6, v254, 29
	v_readlane_b32 s4, v252, 19
	v_readlane_b32 s7, v254, 30
	v_readlane_b32 s5, v252, 20
	v_readlane_b32 s7, v253, 62
	s_movk_i32 s8, 0xc00
	s_cbranch_execz .LBB0_259
	v_lshlrev_b32_e32 v0, 3, v0
	v_lshl_add_u32 v3, s0, 12, v0
	s_mov_b64 s[38:39], 0
.LBB0_258:
	v_ashrrev_i32_e32 v16, 6, v2
	v_bfe_u32 v8, v2, 3, 3
	v_mov_b64_e32 v[4:5], s[88:89]
	v_mad_i64_i32 v[4:5], s[0:1], v16, s82, v[4:5]
	v_lshlrev_b32_e32 v0, 2, v8
	v_lshl_add_u64 v[4:5], v[4:5], 0, v[0:1]
	global_load_dword v20, v[4:5], off
	global_load_dword v21, v[4:5], off offset:32
	global_load_dword v22, v[4:5], off offset:64
	v_mov_b64_e32 v[6:7], s[90:91]
	v_and_b32_e32 v9, 56, v3
	v_mad_i64_i32 v[6:7], s[0:1], v16, s8, v[6:7]
	v_lshlrev_b32_e32 v0, 7, v8
	v_mov_b32_e32 v19, v1
	v_lshlrev_b32_e32 v18, 1, v9
	v_lshl_add_u64 v[4:5], v[6:7], 0, v[0:1]
	v_lshl_add_u64 v[12:13], v[4:5], 0, v[18:19]
	global_load_dwordx4 v[4:7], v[12:13], off
	global_load_dwordx4 v[8:11], v[12:13], off offset:1024
	s_nop 0
	global_load_dwordx4 v[12:15], v[12:13], off offset:2048
	v_ashrrev_i32_e32 v17, 31, v16
	v_lshlrev_b64 v[16:17], 10, v[16:17]
	v_lshl_add_u64 v[16:17], s[4:5], 0, v[16:17]
	v_lshl_add_u64 v[16:17], v[16:17], 0, v[0:1]
	v_lshl_add_u64 v[16:17], v[16:17], 0, v[18:19]
	v_add_u32_e32 v2, 0x200, v2
	s_add_i32 s0, s3, -1
	v_cmp_lt_i32_e32 vcc, s0, v2
	s_or_b64 s[38:39], vcc, s[38:39]
	v_add_u32_e32 v3, s7, v3
	s_waitcnt vmcnt(0)
	v_max3_f32 v0, v20, v21, v22
	v_sub_f32_e32 v18, v20, v0
	v_sub_f32_e32 v19, v21, v0
	v_sub_f32_e32 v0, v22, v0
	v_mul_f32_e32 v30, 0x3fb8aa3b, v18
	v_mul_f32_e32 v31, 0x3fb8aa3b, v19
	v_mul_f32_e32 v0, 0x3fb8aa3b, v0
	v_exp_f32_e32 v30, v30
	v_exp_f32_e32 v31, v31
	v_exp_f32_e32 v32, v0
	v_lshlrev_b32_e32 v22, 16, v8
	v_and_b32_e32 v23, 0xffff0000, v8
	v_add_f32_e32 v0, v30, v31
	v_add_f32_e32 v0, v32, v0
	v_div_scale_f32 v33, s[0:1], v0, v0, 1.0
	v_rcp_f32_e32 v35, v33
	v_div_scale_f32 v34, vcc, 1.0, v0, 1.0
	v_lshlrev_b32_e32 v8, 16, v9
	v_fma_f32 v36, -v33, v35, 1.0
	v_fmac_f32_e32 v35, v36, v35
	v_mul_f32_e32 v36, v34, v35
	v_fma_f32 v37, -v33, v36, v34
	v_fmac_f32_e32 v36, v37, v35
	v_fma_f32 v33, -v33, v36, v34
	v_div_fmas_f32 v33, v33, v35, v36
	v_div_fixup_f32 v33, v33, v0, 1.0
	v_and_b32_e32 v9, 0xffff0000, v9
	v_lshlrev_b32_e32 v24, 16, v10
	v_and_b32_e32 v25, 0xffff0000, v10
	v_lshlrev_b32_e32 v10, 16, v11
	v_and_b32_e32 v11, 0xffff0000, v11
	v_mul_f32_e32 v0, v30, v33
	v_mul_f32_e32 v30, v31, v33
	v_lshlrev_b32_e32 v18, 16, v4
	v_and_b32_e32 v19, 0xffff0000, v4
	v_lshlrev_b32_e32 v4, 16, v5
	v_and_b32_e32 v5, 0xffff0000, v5
	v_lshlrev_b32_e32 v20, 16, v6
	v_and_b32_e32 v21, 0xffff0000, v6
	v_lshlrev_b32_e32 v6, 16, v7
	v_and_b32_e32 v7, 0xffff0000, v7
	v_pk_mul_f32 v[8:9], v[30:31], v[8:9] op_sel_hi:[0,1]
	v_pk_mul_f32 v[22:23], v[30:31], v[22:23] op_sel_hi:[0,1]
	v_pk_mul_f32 v[10:11], v[30:31], v[10:11] op_sel_hi:[0,1]
	v_pk_mul_f32 v[24:25], v[30:31], v[24:25] op_sel_hi:[0,1]
	v_lshlrev_b32_e32 v26, 16, v12
	v_and_b32_e32 v27, 0xffff0000, v12
	v_lshlrev_b32_e32 v12, 16, v13
	v_and_b32_e32 v13, 0xffff0000, v13
	v_lshlrev_b32_e32 v28, 16, v14
	v_and_b32_e32 v29, 0xffff0000, v14
	v_lshlrev_b32_e32 v14, 16, v15
	v_and_b32_e32 v15, 0xffff0000, v15
	v_mul_f32_e32 v32, v32, v33
	v_pk_fma_f32 v[18:19], v[0:1], v[18:19], v[22:23] op_sel_hi:[0,1,1]
	v_pk_fma_f32 v[4:5], v[0:1], v[4:5], v[8:9] op_sel_hi:[0,1,1]
	v_pk_fma_f32 v[8:9], v[0:1], v[20:21], v[24:25] op_sel_hi:[0,1,1]
	v_pk_fma_f32 v[6:7], v[0:1], v[6:7], v[10:11] op_sel_hi:[0,1,1]
	v_pk_fma_f32 v[10:11], v[32:33], v[12:13], v[4:5] op_sel_hi:[0,1,1]
	v_pk_fma_f32 v[4:5], v[32:33], v[26:27], v[18:19] op_sel_hi:[0,1,1]
	v_pk_fma_f32 v[12:13], v[32:33], v[14:15], v[6:7] op_sel_hi:[0,1,1]
	v_pk_fma_f32 v[6:7], v[32:33], v[28:29], v[8:9] op_sel_hi:[0,1,1]
	v_cvt_pk_bf16_f32 v4, v4, v5
	v_cvt_pk_bf16_f32 v5, v10, v11
	v_cvt_pk_bf16_f32 v6, v6, v7
	v_cvt_pk_bf16_f32 v7, v12, v13
	global_store_dwordx4 v[16:17], v[4:7], off
	s_andn2_b64 exec, exec, s[38:39]
	s_cbranch_execnz .LBB0_258
